# EpiAct (FFN-up epilogue) rewritten by hand: packed f32 math, DPP-fused conv taps (v_fmac_f32_dpp), batched ssq/weight loads and shuffles; bit-identical outputs
# speedup vs baseline: 1.0237x; 1.0122x over previous
.LBB0_723:
	v_lshl_add_u32 v184, s6, 8, v186
	v_lshlrev_b32_e32 v146, 6, v184
	v_mov_b32_e32 v147, 0
	v_lshl_add_u64 v[146:147], v[140:141], 0, v[146:147]
	s_mov_b64 s[98:99], 0x2000
	v_lshl_add_u64 v[148:149], v[146:147], 0, s[98:99]
	global_load_dwordx4 v[206:209], v[146:147], off
	global_load_dwordx4 v[210:213], v[146:147], off offset:1024
	global_load_dwordx4 v[214:217], v[146:147], off offset:2048
	global_load_dwordx4 v[218:221], v[146:147], off offset:3072
	global_load_dwordx4 v[222:225], v[148:149], off
	global_load_dwordx4 v[226:229], v[148:149], off offset:1024
	global_load_dwordx4 v[230:233], v[148:149], off offset:2048
	global_load_dwordx4 v[234:237], v[148:149], off offset:3072
	v_lshl_or_b32 v150, s46, 7, v188
	v_mov_b32_e32 v151, 0
	v_lshlrev_b32_e32 v147, 2, v150
	v_mov_b32_e32 v146, v147
	v_mov_b32_e32 v147, 0
	v_lshl_add_u64 v[148:149], s[30:31], 0, v[146:147]
	global_load_dwordx4 v[168:171], v[148:149], off
	global_load_dwordx4 v[192:195], v[148:149], off offset:16
	v_lshl_add_u64 v[148:149], s[0:1], 0, v[146:147]
	global_load_dwordx4 v[172:175], v[148:149], off
	global_load_dwordx4 v[196:199], v[148:149], off offset:16
	v_lshl_add_u64 v[148:149], s[48:49], 0, v[146:147]
	global_load_dwordx4 v[176:179], v[148:149], off
	global_load_dwordx4 v[200:203], v[148:149], off offset:16
	v_lshl_add_u64 v[148:149], s[82:83], 0, v[146:147]
	global_load_dwordx4 v[180:183], v[148:149], off
	global_load_dwordx4 v[238:241], v[148:149], off offset:16
	v_mul_lo_u32 v185, v184, s67
	v_add_lshl_u32 v185, v185, v150, 1
	s_lshl_b32 s5, s6, 2
	s_add_i32 s5, s5, s80
	s_mul_hi_i32 s7, s5, 0x8400
	s_mul_i32 s5, s5, 0x8400
	s_add_u32 s6, s56, s5
	s_addc_u32 s7, s57, s7
	v_lshl_add_u64 v[246:247], v[150:151], 1, s[6:7]
	v_lshl_add_u64 v[246:247], v[246:247], 0, v[138:139]
	v_xor_b32_e32 v148, 16, v191
	v_xor_b32_e32 v149, 32, v191
	v_lshlrev_b32_e32 v148, 2, v148
	v_lshlrev_b32_e32 v149, 2, v149
	s_mov_b32 s98, 0xbfb8aa3b
	s_waitcnt vmcnt(0)
	v_add_f32_e32 v206, v206, v207
	v_add_f32_e32 v208, v208, v209
	v_add_f32_e32 v210, v210, v211
	v_add_f32_e32 v212, v212, v213
	v_add_f32_e32 v214, v214, v215
	v_add_f32_e32 v216, v216, v217
	v_add_f32_e32 v218, v218, v219
	v_add_f32_e32 v220, v220, v221
	v_add_f32_e32 v222, v222, v223
	v_add_f32_e32 v224, v224, v225
	v_add_f32_e32 v226, v226, v227
	v_add_f32_e32 v228, v228, v229
	v_add_f32_e32 v230, v230, v231
	v_add_f32_e32 v232, v232, v233
	v_add_f32_e32 v234, v234, v235
	v_add_f32_e32 v236, v236, v237
	v_add_f32_e32 v206, v206, v208
	v_add_f32_e32 v210, v210, v212
	v_add_f32_e32 v214, v214, v216
	v_add_f32_e32 v218, v218, v220
	v_add_f32_e32 v222, v222, v224
	v_add_f32_e32 v226, v226, v228
	v_add_f32_e32 v230, v230, v232
	v_add_f32_e32 v234, v234, v236
	ds_bpermute_b32 v207, v148, v206
	ds_bpermute_b32 v211, v148, v210
	ds_bpermute_b32 v215, v148, v214
	ds_bpermute_b32 v219, v148, v218
	ds_bpermute_b32 v223, v148, v222
	ds_bpermute_b32 v227, v148, v226
	ds_bpermute_b32 v231, v148, v230
	ds_bpermute_b32 v235, v148, v234
	s_waitcnt lgkmcnt(0)
	v_add_f32_e32 v206, v206, v207
	v_add_f32_e32 v210, v210, v211
	v_add_f32_e32 v214, v214, v215
	v_add_f32_e32 v218, v218, v219
	v_add_f32_e32 v222, v222, v223
	v_add_f32_e32 v226, v226, v227
	v_add_f32_e32 v230, v230, v231
	v_add_f32_e32 v234, v234, v235
	ds_bpermute_b32 v207, v149, v206
	ds_bpermute_b32 v211, v149, v210
	ds_bpermute_b32 v215, v149, v214
	ds_bpermute_b32 v219, v149, v218
	ds_bpermute_b32 v223, v149, v222
	ds_bpermute_b32 v227, v149, v226
	ds_bpermute_b32 v231, v149, v230
	ds_bpermute_b32 v235, v149, v234
	s_waitcnt lgkmcnt(0)
	v_add_f32_e32 v206, v206, v207
	v_add_f32_e32 v210, v210, v211
	v_add_f32_e32 v214, v214, v215
	v_add_f32_e32 v218, v218, v219
	v_add_f32_e32 v222, v222, v223
	v_add_f32_e32 v226, v226, v227
	v_add_f32_e32 v230, v230, v231
	v_add_f32_e32 v234, v234, v235
	v_pk_mul_f32 v[168:169], v[168:169], s[98:99] op_sel_hi:[1,0]
	v_pk_mul_f32 v[170:171], v[170:171], s[98:99] op_sel_hi:[1,0]
	v_pk_mul_f32 v[172:173], v[172:173], s[98:99] op_sel_hi:[1,0]
	v_pk_mul_f32 v[174:175], v[174:175], s[98:99] op_sel_hi:[1,0]
	v_pk_mul_f32 v[176:177], v[176:177], s[98:99] op_sel_hi:[1,0]
	v_pk_mul_f32 v[178:179], v[178:179], s[98:99] op_sel_hi:[1,0]
	v_pk_mul_f32 v[180:181], v[180:181], s[98:99] op_sel_hi:[1,0]
	v_pk_mul_f32 v[182:183], v[182:183], s[98:99] op_sel_hi:[1,0]
	v_pk_mul_f32 v[192:193], v[192:193], s[98:99] op_sel_hi:[1,0]
	v_pk_mul_f32 v[194:195], v[194:195], s[98:99] op_sel_hi:[1,0]
	v_pk_mul_f32 v[196:197], v[196:197], s[98:99] op_sel_hi:[1,0]
	v_pk_mul_f32 v[198:199], v[198:199], s[98:99] op_sel_hi:[1,0]
	v_pk_mul_f32 v[200:201], v[200:201], s[98:99] op_sel_hi:[1,0]
	v_pk_mul_f32 v[202:203], v[202:203], s[98:99] op_sel_hi:[1,0]
	v_pk_mul_f32 v[238:239], v[238:239], s[98:99] op_sel_hi:[1,0]
	v_pk_mul_f32 v[240:241], v[240:241], s[98:99] op_sel_hi:[1,0]
	v_fmamk_f32 v206, v206, 0x3a800000, v154
	v_cmp_gt_f32_e32 vcc, s84, v206
	v_mul_f32_e32 v207, 0x4b800000, v206
	s_nop 0
	v_cndmask_b32_e32 v206, v206, v207, vcc
	v_rsq_f32_e32 v206, v206
	s_nop 0
	v_mul_f32_e32 v207, 0x45800000, v206
	v_cndmask_b32_e32 v206, v206, v207, vcc
	v_mul_f32_e32 v208, 0xbf317218, v206
	v_fmamk_f32 v210, v210, 0x3a800000, v154
	v_cmp_gt_f32_e32 vcc, s84, v210
	v_mul_f32_e32 v211, 0x4b800000, v210
	s_nop 0
	v_cndmask_b32_e32 v210, v210, v211, vcc
	v_rsq_f32_e32 v210, v210
	s_nop 0
	v_mul_f32_e32 v211, 0x45800000, v210
	v_cndmask_b32_e32 v210, v210, v211, vcc
	v_mul_f32_e32 v212, 0xbf317218, v210
	v_fmamk_f32 v214, v214, 0x3a800000, v154
	v_cmp_gt_f32_e32 vcc, s84, v214
	v_mul_f32_e32 v215, 0x4b800000, v214
	s_nop 0
	v_cndmask_b32_e32 v214, v214, v215, vcc
	v_rsq_f32_e32 v214, v214
	s_nop 0
	v_mul_f32_e32 v215, 0x45800000, v214
	v_cndmask_b32_e32 v214, v214, v215, vcc
	v_mul_f32_e32 v216, 0xbf317218, v214
	v_fmamk_f32 v218, v218, 0x3a800000, v154
	v_cmp_gt_f32_e32 vcc, s84, v218
	v_mul_f32_e32 v219, 0x4b800000, v218
	s_nop 0
	v_cndmask_b32_e32 v218, v218, v219, vcc
	v_rsq_f32_e32 v218, v218
	s_nop 0
	v_mul_f32_e32 v219, 0x45800000, v218
	v_cndmask_b32_e32 v218, v218, v219, vcc
	v_mul_f32_e32 v220, 0xbf317218, v218
	v_fmamk_f32 v222, v222, 0x3a800000, v154
	v_cmp_gt_f32_e32 vcc, s84, v222
	v_mul_f32_e32 v223, 0x4b800000, v222
	s_nop 0
	v_cndmask_b32_e32 v222, v222, v223, vcc
	v_rsq_f32_e32 v222, v222
	s_nop 0
	v_mul_f32_e32 v223, 0x45800000, v222
	v_cndmask_b32_e32 v222, v222, v223, vcc
	v_mul_f32_e32 v224, 0xbf317218, v222
	v_fmamk_f32 v226, v226, 0x3a800000, v154
	v_cmp_gt_f32_e32 vcc, s84, v226
	v_mul_f32_e32 v227, 0x4b800000, v226
	s_nop 0
	v_cndmask_b32_e32 v226, v226, v227, vcc
	v_rsq_f32_e32 v226, v226
	s_nop 0
	v_mul_f32_e32 v227, 0x45800000, v226
	v_cndmask_b32_e32 v226, v226, v227, vcc
	v_mul_f32_e32 v228, 0xbf317218, v226
	v_fmamk_f32 v230, v230, 0x3a800000, v154
	v_cmp_gt_f32_e32 vcc, s84, v230
	v_mul_f32_e32 v231, 0x4b800000, v230
	s_nop 0
	v_cndmask_b32_e32 v230, v230, v231, vcc
	v_rsq_f32_e32 v230, v230
	s_nop 0
	v_mul_f32_e32 v231, 0x45800000, v230
	v_cndmask_b32_e32 v230, v230, v231, vcc
	v_mul_f32_e32 v232, 0xbf317218, v230
	v_fmamk_f32 v234, v234, 0x3a800000, v154
	v_cmp_gt_f32_e32 vcc, s84, v234
	v_mul_f32_e32 v235, 0x4b800000, v234
	s_nop 0
	v_cndmask_b32_e32 v234, v234, v235, vcc
	v_rsq_f32_e32 v234, v234
	s_nop 0
	v_mul_f32_e32 v235, 0x45800000, v234
	v_cndmask_b32_e32 v234, v234, v235, vcc
	v_mul_f32_e32 v236, 0xbf317218, v234
	s_and_saveexec_b64 s[6:7], s[40:41]
	v_pk_mul_f32 v[242:243], v[124:125], v[206:207] op_sel_hi:[1,0]
	v_pk_mul_f32 v[244:245], v[126:127], v[206:207] op_sel_hi:[1,0]
	s_mov_b32 s98, 0x5800
	s_mov_b32 s99, 0
	v_cvt_pk_bf16_f32 v242, v242, v243
	v_cvt_pk_bf16_f32 v243, v244, v245
	v_lshl_add_u64 v[150:151], v[246:247], 0, s[98:99]
	global_store_dwordx2 v[150:151], v[242:243], off
	s_or_b64 exec, exec, s[6:7]
	v_pk_mul_f32 v[128:129], v[128:129], v[206:207] op_sel_hi:[1,0]
	v_pk_mul_f32 v[130:131], v[130:131], v[206:207] op_sel_hi:[1,0]
	v_pk_mul_f32 v[124:125], v[124:125], v[208:209] op_sel_hi:[1,0]
	v_pk_mul_f32 v[126:127], v[126:127], v[208:209] op_sel_hi:[1,0]
	v_pk_fma_f32 v[146:147], v[176:177], v[128:129], v[180:181]
	v_pk_fma_f32 v[148:149], v[178:179], v[130:131], v[182:183]
	v_fmac_f32_dpp v146, v128, v172 row_shr:1 row_mask:0xf bank_mask:0xf bound_ctrl:1
	v_fmac_f32_dpp v147, v129, v173 row_shr:1 row_mask:0xf bank_mask:0xf bound_ctrl:1
	v_fmac_f32_dpp v148, v130, v174 row_shr:1 row_mask:0xf bank_mask:0xf bound_ctrl:1
	v_fmac_f32_dpp v149, v131, v175 row_shr:1 row_mask:0xf bank_mask:0xf bound_ctrl:1
	v_fmac_f32_dpp v146, v128, v168 row_shr:2 row_mask:0xf bank_mask:0xf bound_ctrl:1
	v_fmac_f32_dpp v147, v129, v169 row_shr:2 row_mask:0xf bank_mask:0xf bound_ctrl:1
	v_fmac_f32_dpp v148, v130, v170 row_shr:2 row_mask:0xf bank_mask:0xf bound_ctrl:1
	v_fmac_f32_dpp v149, v131, v171 row_shr:2 row_mask:0xf bank_mask:0xf bound_ctrl:1
	v_exp_f32_e32 v242, v146
	v_exp_f32_e32 v243, v147
	v_exp_f32_e32 v244, v148
	v_exp_f32_e32 v245, v149
	v_pk_mul_f32 v[146:147], v[146:147], v[124:125]
	v_pk_mul_f32 v[148:149], v[148:149], v[126:127]
	v_pk_add_f32 v[242:243], v[242:243], 1.0 op_sel_hi:[1,0]
	v_pk_add_f32 v[244:245], v[244:245], 1.0 op_sel_hi:[1,0]
	v_rcp_f32_e32 v242, v242
	v_rcp_f32_e32 v243, v243
	v_rcp_f32_e32 v244, v244
	v_rcp_f32_e32 v245, v245
	v_cvt_pk_bf16_f32 v126, v128, v129
	v_cvt_pk_bf16_f32 v127, v130, v131
	v_pk_mul_f32 v[146:147], v[146:147], v[242:243]
	v_pk_mul_f32 v[148:149], v[148:149], v[244:245]
	s_mov_b32 s98, 0x2c00
	s_mov_b32 s99, 0
	s_and_saveexec_b64 s[6:7], s[40:41]
	v_lshl_add_u64 v[150:151], v[246:247], 0, s[98:99]
	global_store_dwordx2 v[150:151], v[126:127], off
	s_or_b64 exec, exec, s[6:7]
	v_cvt_pk_bf16_f32 v124, v146, v147
	v_cvt_pk_bf16_f32 v125, v148, v149
	v_pk_mul_f32 v[120:121], v[120:121], v[210:211] op_sel_hi:[1,0]
	v_pk_mul_f32 v[122:123], v[122:123], v[210:211] op_sel_hi:[1,0]
	v_pk_mul_f32 v[116:117], v[116:117], v[212:213] op_sel_hi:[1,0]
	v_pk_mul_f32 v[118:119], v[118:119], v[212:213] op_sel_hi:[1,0]
	v_pk_fma_f32 v[146:147], v[176:177], v[120:121], v[180:181]
	v_pk_fma_f32 v[148:149], v[178:179], v[122:123], v[182:183]
	v_fmac_f32_dpp v146, v120, v172 row_shr:1 row_mask:0xf bank_mask:0xf bound_ctrl:1
	v_fmac_f32_dpp v147, v121, v173 row_shr:1 row_mask:0xf bank_mask:0xf bound_ctrl:1
	v_fmac_f32_dpp v148, v122, v174 row_shr:1 row_mask:0xf bank_mask:0xf bound_ctrl:1
	v_fmac_f32_dpp v149, v123, v175 row_shr:1 row_mask:0xf bank_mask:0xf bound_ctrl:1
	v_fmac_f32_dpp v146, v128, v172 row_shl:15 row_mask:0xf bank_mask:0xf
	v_fmac_f32_dpp v147, v129, v173 row_shl:15 row_mask:0xf bank_mask:0xf
	v_fmac_f32_dpp v148, v130, v174 row_shl:15 row_mask:0xf bank_mask:0xf
	v_fmac_f32_dpp v149, v131, v175 row_shl:15 row_mask:0xf bank_mask:0xf
	v_fmac_f32_dpp v146, v120, v168 row_shr:2 row_mask:0xf bank_mask:0xf bound_ctrl:1
	v_fmac_f32_dpp v147, v121, v169 row_shr:2 row_mask:0xf bank_mask:0xf bound_ctrl:1
	v_fmac_f32_dpp v148, v122, v170 row_shr:2 row_mask:0xf bank_mask:0xf bound_ctrl:1
	v_fmac_f32_dpp v149, v123, v171 row_shr:2 row_mask:0xf bank_mask:0xf bound_ctrl:1
	v_fmac_f32_dpp v146, v128, v168 row_shl:14 row_mask:0xf bank_mask:0xf
	v_fmac_f32_dpp v147, v129, v169 row_shl:14 row_mask:0xf bank_mask:0xf
	v_fmac_f32_dpp v148, v130, v170 row_shl:14 row_mask:0xf bank_mask:0xf
	v_fmac_f32_dpp v149, v131, v171 row_shl:14 row_mask:0xf bank_mask:0xf
	v_exp_f32_e32 v242, v146
	v_exp_f32_e32 v243, v147
	v_exp_f32_e32 v244, v148
	v_exp_f32_e32 v245, v149
	v_pk_mul_f32 v[146:147], v[146:147], v[116:117]
	v_pk_mul_f32 v[148:149], v[148:149], v[118:119]
	v_pk_add_f32 v[242:243], v[242:243], 1.0 op_sel_hi:[1,0]
	v_pk_add_f32 v[244:245], v[244:245], 1.0 op_sel_hi:[1,0]
	v_rcp_f32_e32 v242, v242
	v_rcp_f32_e32 v243, v243
	v_rcp_f32_e32 v244, v244
	v_rcp_f32_e32 v245, v245
	s_nop 0
	v_pk_mul_f32 v[146:147], v[146:147], v[242:243]
	v_pk_mul_f32 v[148:149], v[148:149], v[244:245]
	v_cvt_pk_bf16_f32 v116, v146, v147
	v_cvt_pk_bf16_f32 v117, v148, v149
	v_pk_mul_f32 v[112:113], v[112:113], v[214:215] op_sel_hi:[1,0]
	v_pk_mul_f32 v[114:115], v[114:115], v[214:215] op_sel_hi:[1,0]
	v_pk_mul_f32 v[98:99], v[98:99], v[216:217] op_sel_hi:[1,0]
	v_pk_mul_f32 v[100:101], v[100:101], v[216:217] op_sel_hi:[1,0]
	v_pk_fma_f32 v[146:147], v[176:177], v[112:113], v[180:181]
	v_pk_fma_f32 v[148:149], v[178:179], v[114:115], v[182:183]
	v_fmac_f32_dpp v146, v112, v172 row_shr:1 row_mask:0xf bank_mask:0xf bound_ctrl:1
	v_fmac_f32_dpp v147, v113, v173 row_shr:1 row_mask:0xf bank_mask:0xf bound_ctrl:1
	v_fmac_f32_dpp v148, v114, v174 row_shr:1 row_mask:0xf bank_mask:0xf bound_ctrl:1
	v_fmac_f32_dpp v149, v115, v175 row_shr:1 row_mask:0xf bank_mask:0xf bound_ctrl:1
	v_fmac_f32_dpp v146, v120, v172 row_shl:15 row_mask:0xf bank_mask:0xf
	v_fmac_f32_dpp v147, v121, v173 row_shl:15 row_mask:0xf bank_mask:0xf
	v_fmac_f32_dpp v148, v122, v174 row_shl:15 row_mask:0xf bank_mask:0xf
	v_fmac_f32_dpp v149, v123, v175 row_shl:15 row_mask:0xf bank_mask:0xf
	v_fmac_f32_dpp v146, v112, v168 row_shr:2 row_mask:0xf bank_mask:0xf bound_ctrl:1
	v_fmac_f32_dpp v147, v113, v169 row_shr:2 row_mask:0xf bank_mask:0xf bound_ctrl:1
	v_fmac_f32_dpp v148, v114, v170 row_shr:2 row_mask:0xf bank_mask:0xf bound_ctrl:1
	v_fmac_f32_dpp v149, v115, v171 row_shr:2 row_mask:0xf bank_mask:0xf bound_ctrl:1
	v_fmac_f32_dpp v146, v120, v168 row_shl:14 row_mask:0xf bank_mask:0xf
	v_fmac_f32_dpp v147, v121, v169 row_shl:14 row_mask:0xf bank_mask:0xf
	v_fmac_f32_dpp v148, v122, v170 row_shl:14 row_mask:0xf bank_mask:0xf
	v_fmac_f32_dpp v149, v123, v171 row_shl:14 row_mask:0xf bank_mask:0xf
	v_exp_f32_e32 v242, v146
	v_exp_f32_e32 v243, v147
	v_exp_f32_e32 v244, v148
	v_exp_f32_e32 v245, v149
	v_pk_mul_f32 v[146:147], v[146:147], v[98:99]
	v_pk_mul_f32 v[148:149], v[148:149], v[100:101]
	v_pk_add_f32 v[242:243], v[242:243], 1.0 op_sel_hi:[1,0]
	v_pk_add_f32 v[244:245], v[244:245], 1.0 op_sel_hi:[1,0]
	v_rcp_f32_e32 v242, v242
	v_rcp_f32_e32 v243, v243
	v_rcp_f32_e32 v244, v244
	v_rcp_f32_e32 v245, v245
	s_nop 0
	v_pk_mul_f32 v[146:147], v[146:147], v[242:243]
	v_pk_mul_f32 v[148:149], v[148:149], v[244:245]
	v_cvt_pk_bf16_f32 v98, v146, v147
	v_cvt_pk_bf16_f32 v99, v148, v149
	v_pk_mul_f32 v[108:109], v[108:109], v[218:219] op_sel_hi:[1,0]
	v_pk_mul_f32 v[110:111], v[110:111], v[218:219] op_sel_hi:[1,0]
	v_pk_mul_f32 v[104:105], v[104:105], v[220:221] op_sel_hi:[1,0]
	v_pk_mul_f32 v[106:107], v[106:107], v[220:221] op_sel_hi:[1,0]
	v_pk_fma_f32 v[146:147], v[176:177], v[108:109], v[180:181]
	v_pk_fma_f32 v[148:149], v[178:179], v[110:111], v[182:183]
	v_fmac_f32_dpp v146, v108, v172 row_shr:1 row_mask:0xf bank_mask:0xf bound_ctrl:1
	v_fmac_f32_dpp v147, v109, v173 row_shr:1 row_mask:0xf bank_mask:0xf bound_ctrl:1
	v_fmac_f32_dpp v148, v110, v174 row_shr:1 row_mask:0xf bank_mask:0xf bound_ctrl:1
	v_fmac_f32_dpp v149, v111, v175 row_shr:1 row_mask:0xf bank_mask:0xf bound_ctrl:1
	v_fmac_f32_dpp v146, v112, v172 row_shl:15 row_mask:0xf bank_mask:0xf
	v_fmac_f32_dpp v147, v113, v173 row_shl:15 row_mask:0xf bank_mask:0xf
	v_fmac_f32_dpp v148, v114, v174 row_shl:15 row_mask:0xf bank_mask:0xf
	v_fmac_f32_dpp v149, v115, v175 row_shl:15 row_mask:0xf bank_mask:0xf
	v_fmac_f32_dpp v146, v108, v168 row_shr:2 row_mask:0xf bank_mask:0xf bound_ctrl:1
	v_fmac_f32_dpp v147, v109, v169 row_shr:2 row_mask:0xf bank_mask:0xf bound_ctrl:1
	v_fmac_f32_dpp v148, v110, v170 row_shr:2 row_mask:0xf bank_mask:0xf bound_ctrl:1
	v_fmac_f32_dpp v149, v111, v171 row_shr:2 row_mask:0xf bank_mask:0xf bound_ctrl:1
	v_fmac_f32_dpp v146, v112, v168 row_shl:14 row_mask:0xf bank_mask:0xf
	v_fmac_f32_dpp v147, v113, v169 row_shl:14 row_mask:0xf bank_mask:0xf
	v_fmac_f32_dpp v148, v114, v170 row_shl:14 row_mask:0xf bank_mask:0xf
	v_fmac_f32_dpp v149, v115, v171 row_shl:14 row_mask:0xf bank_mask:0xf
	v_exp_f32_e32 v242, v146
	v_exp_f32_e32 v243, v147
	v_exp_f32_e32 v244, v148
	v_exp_f32_e32 v245, v149
	v_pk_mul_f32 v[146:147], v[146:147], v[104:105]
	v_pk_mul_f32 v[148:149], v[148:149], v[106:107]
	v_pk_add_f32 v[242:243], v[242:243], 1.0 op_sel_hi:[1,0]
	v_pk_add_f32 v[244:245], v[244:245], 1.0 op_sel_hi:[1,0]
	v_rcp_f32_e32 v242, v242
	v_rcp_f32_e32 v243, v243
	v_rcp_f32_e32 v244, v244
	v_rcp_f32_e32 v245, v245
	v_cvt_pk_bf16_f32 v106, v108, v109
	v_cvt_pk_bf16_f32 v107, v110, v111
	v_pk_mul_f32 v[146:147], v[146:147], v[242:243]
	v_pk_mul_f32 v[148:149], v[148:149], v[244:245]
	s_mov_b32 s98, 0xfffecc00
	s_mov_b32 s99, -1
	s_and_saveexec_b64 s[6:7], s[42:43]
	v_lshl_add_u64 v[150:151], v[246:247], 0, s[98:99]
	global_store_dwordx2 v[150:151], v[106:107], off
	s_or_b64 exec, exec, s[6:7]
	v_cvt_pk_bf16_f32 v104, v146, v147
	v_cvt_pk_bf16_f32 v105, v148, v149
	s_and_saveexec_b64 s[6:7], s[40:41]
	v_pk_mul_f32 v[242:243], v[88:89], v[222:223] op_sel_hi:[1,0]
	v_pk_mul_f32 v[244:245], v[90:91], v[222:223] op_sel_hi:[1,0]
	s_mov_b32 s98, 0x16000
	s_mov_b32 s99, 0
	v_cvt_pk_bf16_f32 v242, v242, v243
	v_cvt_pk_bf16_f32 v243, v244, v245
	v_lshl_add_u64 v[150:151], v[246:247], 0, s[98:99]
	global_store_dwordx2 v[150:151], v[242:243], off
	s_or_b64 exec, exec, s[6:7]
	v_pk_mul_f32 v[94:95], v[94:95], v[222:223] op_sel_hi:[1,0]
	v_pk_mul_f32 v[96:97], v[96:97], v[222:223] op_sel_hi:[1,0]
	v_pk_mul_f32 v[88:89], v[88:89], v[224:225] op_sel_hi:[1,0]
	v_pk_mul_f32 v[90:91], v[90:91], v[224:225] op_sel_hi:[1,0]
	v_pk_fma_f32 v[146:147], v[176:177], v[94:95], v[180:181]
	v_pk_fma_f32 v[148:149], v[178:179], v[96:97], v[182:183]
	v_fmac_f32_dpp v146, v94, v172 row_shr:1 row_mask:0xf bank_mask:0xf bound_ctrl:1
	v_fmac_f32_dpp v147, v95, v173 row_shr:1 row_mask:0xf bank_mask:0xf bound_ctrl:1
	v_fmac_f32_dpp v148, v96, v174 row_shr:1 row_mask:0xf bank_mask:0xf bound_ctrl:1
	v_fmac_f32_dpp v149, v97, v175 row_shr:1 row_mask:0xf bank_mask:0xf bound_ctrl:1
	v_fmac_f32_dpp v146, v94, v168 row_shr:2 row_mask:0xf bank_mask:0xf bound_ctrl:1
	v_fmac_f32_dpp v147, v95, v169 row_shr:2 row_mask:0xf bank_mask:0xf bound_ctrl:1
	v_fmac_f32_dpp v148, v96, v170 row_shr:2 row_mask:0xf bank_mask:0xf bound_ctrl:1
	v_fmac_f32_dpp v149, v97, v171 row_shr:2 row_mask:0xf bank_mask:0xf bound_ctrl:1
	v_exp_f32_e32 v242, v146
	v_exp_f32_e32 v243, v147
	v_exp_f32_e32 v244, v148
	v_exp_f32_e32 v245, v149
	v_pk_mul_f32 v[146:147], v[146:147], v[88:89]
	v_pk_mul_f32 v[148:149], v[148:149], v[90:91]
	v_pk_add_f32 v[242:243], v[242:243], 1.0 op_sel_hi:[1,0]
	v_pk_add_f32 v[244:245], v[244:245], 1.0 op_sel_hi:[1,0]
	v_rcp_f32_e32 v242, v242
	v_rcp_f32_e32 v243, v243
	v_rcp_f32_e32 v244, v244
	v_rcp_f32_e32 v245, v245
	v_cvt_pk_bf16_f32 v90, v94, v95
	v_cvt_pk_bf16_f32 v91, v96, v97
	v_pk_mul_f32 v[146:147], v[146:147], v[242:243]
	v_pk_mul_f32 v[148:149], v[148:149], v[244:245]
	s_mov_b32 s98, 0x13400
	s_mov_b32 s99, 0
	s_and_saveexec_b64 s[6:7], s[40:41]
	v_lshl_add_u64 v[150:151], v[246:247], 0, s[98:99]
	global_store_dwordx2 v[150:151], v[90:91], off
	s_or_b64 exec, exec, s[6:7]
	v_cvt_pk_bf16_f32 v88, v146, v147
	v_cvt_pk_bf16_f32 v89, v148, v149
	v_pk_mul_f32 v[84:85], v[84:85], v[226:227] op_sel_hi:[1,0]
	v_pk_mul_f32 v[86:87], v[86:87], v[226:227] op_sel_hi:[1,0]
	v_pk_mul_f32 v[80:81], v[80:81], v[228:229] op_sel_hi:[1,0]
	v_pk_mul_f32 v[82:83], v[82:83], v[228:229] op_sel_hi:[1,0]
	v_pk_fma_f32 v[146:147], v[176:177], v[84:85], v[180:181]
	v_pk_fma_f32 v[148:149], v[178:179], v[86:87], v[182:183]
	v_fmac_f32_dpp v146, v84, v172 row_shr:1 row_mask:0xf bank_mask:0xf bound_ctrl:1
	v_fmac_f32_dpp v147, v85, v173 row_shr:1 row_mask:0xf bank_mask:0xf bound_ctrl:1
	v_fmac_f32_dpp v148, v86, v174 row_shr:1 row_mask:0xf bank_mask:0xf bound_ctrl:1
	v_fmac_f32_dpp v149, v87, v175 row_shr:1 row_mask:0xf bank_mask:0xf bound_ctrl:1
	v_fmac_f32_dpp v146, v94, v172 row_shl:15 row_mask:0xf bank_mask:0xf
	v_fmac_f32_dpp v147, v95, v173 row_shl:15 row_mask:0xf bank_mask:0xf
	v_fmac_f32_dpp v148, v96, v174 row_shl:15 row_mask:0xf bank_mask:0xf
	v_fmac_f32_dpp v149, v97, v175 row_shl:15 row_mask:0xf bank_mask:0xf
	v_fmac_f32_dpp v146, v84, v168 row_shr:2 row_mask:0xf bank_mask:0xf bound_ctrl:1
	v_fmac_f32_dpp v147, v85, v169 row_shr:2 row_mask:0xf bank_mask:0xf bound_ctrl:1
	v_fmac_f32_dpp v148, v86, v170 row_shr:2 row_mask:0xf bank_mask:0xf bound_ctrl:1
	v_fmac_f32_dpp v149, v87, v171 row_shr:2 row_mask:0xf bank_mask:0xf bound_ctrl:1
	v_fmac_f32_dpp v146, v94, v168 row_shl:14 row_mask:0xf bank_mask:0xf
	v_fmac_f32_dpp v147, v95, v169 row_shl:14 row_mask:0xf bank_mask:0xf
	v_fmac_f32_dpp v148, v96, v170 row_shl:14 row_mask:0xf bank_mask:0xf
	v_fmac_f32_dpp v149, v97, v171 row_shl:14 row_mask:0xf bank_mask:0xf
	v_exp_f32_e32 v242, v146
	v_exp_f32_e32 v243, v147
	v_exp_f32_e32 v244, v148
	v_exp_f32_e32 v245, v149
	v_pk_mul_f32 v[146:147], v[146:147], v[80:81]
	v_pk_mul_f32 v[148:149], v[148:149], v[82:83]
	v_pk_add_f32 v[242:243], v[242:243], 1.0 op_sel_hi:[1,0]
	v_pk_add_f32 v[244:245], v[244:245], 1.0 op_sel_hi:[1,0]
	v_rcp_f32_e32 v242, v242
	v_rcp_f32_e32 v243, v243
	v_rcp_f32_e32 v244, v244
	v_rcp_f32_e32 v245, v245
	s_nop 0
	v_pk_mul_f32 v[146:147], v[146:147], v[242:243]
	v_pk_mul_f32 v[148:149], v[148:149], v[244:245]
	v_cvt_pk_bf16_f32 v80, v146, v147
	v_cvt_pk_bf16_f32 v81, v148, v149
	v_pk_mul_f32 v[76:77], v[76:77], v[230:231] op_sel_hi:[1,0]
	v_pk_mul_f32 v[78:79], v[78:79], v[230:231] op_sel_hi:[1,0]
	v_pk_mul_f32 v[72:73], v[72:73], v[232:233] op_sel_hi:[1,0]
	v_pk_mul_f32 v[74:75], v[74:75], v[232:233] op_sel_hi:[1,0]
	v_pk_fma_f32 v[146:147], v[176:177], v[76:77], v[180:181]
	v_pk_fma_f32 v[148:149], v[178:179], v[78:79], v[182:183]
	v_fmac_f32_dpp v146, v76, v172 row_shr:1 row_mask:0xf bank_mask:0xf bound_ctrl:1
	v_fmac_f32_dpp v147, v77, v173 row_shr:1 row_mask:0xf bank_mask:0xf bound_ctrl:1
	v_fmac_f32_dpp v148, v78, v174 row_shr:1 row_mask:0xf bank_mask:0xf bound_ctrl:1
	v_fmac_f32_dpp v149, v79, v175 row_shr:1 row_mask:0xf bank_mask:0xf bound_ctrl:1
	v_fmac_f32_dpp v146, v84, v172 row_shl:15 row_mask:0xf bank_mask:0xf
	v_fmac_f32_dpp v147, v85, v173 row_shl:15 row_mask:0xf bank_mask:0xf
	v_fmac_f32_dpp v148, v86, v174 row_shl:15 row_mask:0xf bank_mask:0xf
	v_fmac_f32_dpp v149, v87, v175 row_shl:15 row_mask:0xf bank_mask:0xf
	v_fmac_f32_dpp v146, v76, v168 row_shr:2 row_mask:0xf bank_mask:0xf bound_ctrl:1
	v_fmac_f32_dpp v147, v77, v169 row_shr:2 row_mask:0xf bank_mask:0xf bound_ctrl:1
	v_fmac_f32_dpp v148, v78, v170 row_shr:2 row_mask:0xf bank_mask:0xf bound_ctrl:1
	v_fmac_f32_dpp v149, v79, v171 row_shr:2 row_mask:0xf bank_mask:0xf bound_ctrl:1
	v_fmac_f32_dpp v146, v84, v168 row_shl:14 row_mask:0xf bank_mask:0xf
	v_fmac_f32_dpp v147, v85, v169 row_shl:14 row_mask:0xf bank_mask:0xf
	v_fmac_f32_dpp v148, v86, v170 row_shl:14 row_mask:0xf bank_mask:0xf
	v_fmac_f32_dpp v149, v87, v171 row_shl:14 row_mask:0xf bank_mask:0xf
	v_exp_f32_e32 v242, v146
	v_exp_f32_e32 v243, v147
	v_exp_f32_e32 v244, v148
	v_exp_f32_e32 v245, v149
	v_pk_mul_f32 v[146:147], v[146:147], v[72:73]
	v_pk_mul_f32 v[148:149], v[148:149], v[74:75]
	v_pk_add_f32 v[242:243], v[242:243], 1.0 op_sel_hi:[1,0]
	v_pk_add_f32 v[244:245], v[244:245], 1.0 op_sel_hi:[1,0]
	v_rcp_f32_e32 v242, v242
	v_rcp_f32_e32 v243, v243
	v_rcp_f32_e32 v244, v244
	v_rcp_f32_e32 v245, v245
	s_nop 0
	v_pk_mul_f32 v[146:147], v[146:147], v[242:243]
	v_pk_mul_f32 v[148:149], v[148:149], v[244:245]
	v_cvt_pk_bf16_f32 v72, v146, v147
	v_cvt_pk_bf16_f32 v73, v148, v149
	v_pk_mul_f32 v[68:69], v[68:69], v[234:235] op_sel_hi:[1,0]
	v_pk_mul_f32 v[70:71], v[70:71], v[234:235] op_sel_hi:[1,0]
	v_pk_mul_f32 v[64:65], v[64:65], v[236:237] op_sel_hi:[1,0]
	v_pk_mul_f32 v[66:67], v[66:67], v[236:237] op_sel_hi:[1,0]
	v_pk_fma_f32 v[146:147], v[176:177], v[68:69], v[180:181]
	v_pk_fma_f32 v[148:149], v[178:179], v[70:71], v[182:183]
	v_fmac_f32_dpp v146, v68, v172 row_shr:1 row_mask:0xf bank_mask:0xf bound_ctrl:1
	v_fmac_f32_dpp v147, v69, v173 row_shr:1 row_mask:0xf bank_mask:0xf bound_ctrl:1
	v_fmac_f32_dpp v148, v70, v174 row_shr:1 row_mask:0xf bank_mask:0xf bound_ctrl:1
	v_fmac_f32_dpp v149, v71, v175 row_shr:1 row_mask:0xf bank_mask:0xf bound_ctrl:1
	v_fmac_f32_dpp v146, v76, v172 row_shl:15 row_mask:0xf bank_mask:0xf
	v_fmac_f32_dpp v147, v77, v173 row_shl:15 row_mask:0xf bank_mask:0xf
	v_fmac_f32_dpp v148, v78, v174 row_shl:15 row_mask:0xf bank_mask:0xf
	v_fmac_f32_dpp v149, v79, v175 row_shl:15 row_mask:0xf bank_mask:0xf
	v_fmac_f32_dpp v146, v68, v168 row_shr:2 row_mask:0xf bank_mask:0xf bound_ctrl:1
	v_fmac_f32_dpp v147, v69, v169 row_shr:2 row_mask:0xf bank_mask:0xf bound_ctrl:1
	v_fmac_f32_dpp v148, v70, v170 row_shr:2 row_mask:0xf bank_mask:0xf bound_ctrl:1
	v_fmac_f32_dpp v149, v71, v171 row_shr:2 row_mask:0xf bank_mask:0xf bound_ctrl:1
	v_fmac_f32_dpp v146, v76, v168 row_shl:14 row_mask:0xf bank_mask:0xf
	v_fmac_f32_dpp v147, v77, v169 row_shl:14 row_mask:0xf bank_mask:0xf
	v_fmac_f32_dpp v148, v78, v170 row_shl:14 row_mask:0xf bank_mask:0xf
	v_fmac_f32_dpp v149, v79, v171 row_shl:14 row_mask:0xf bank_mask:0xf
	v_exp_f32_e32 v242, v146
	v_exp_f32_e32 v243, v147
	v_exp_f32_e32 v244, v148
	v_exp_f32_e32 v245, v149
	v_pk_mul_f32 v[146:147], v[146:147], v[64:65]
	v_pk_mul_f32 v[148:149], v[148:149], v[66:67]
	v_pk_add_f32 v[242:243], v[242:243], 1.0 op_sel_hi:[1,0]
	v_pk_add_f32 v[244:245], v[244:245], 1.0 op_sel_hi:[1,0]
	v_rcp_f32_e32 v242, v242
	v_rcp_f32_e32 v243, v243
	v_rcp_f32_e32 v244, v244
	v_rcp_f32_e32 v245, v245
	v_cvt_pk_bf16_f32 v66, v68, v69
	v_cvt_pk_bf16_f32 v67, v70, v71
	v_pk_mul_f32 v[146:147], v[146:147], v[242:243]
	v_pk_mul_f32 v[148:149], v[148:149], v[244:245]
	s_mov_b32 s98, 0xffffd400
	s_mov_b32 s99, -1
	s_and_saveexec_b64 s[6:7], s[42:43]
	v_lshl_add_u64 v[150:151], v[246:247], 0, s[98:99]
	global_store_dwordx2 v[150:151], v[66:67], off
	s_or_b64 exec, exec, s[6:7]
	v_cvt_pk_bf16_f32 v64, v146, v147
	v_cvt_pk_bf16_f32 v65, v148, v149
	s_and_saveexec_b64 s[6:7], s[40:41]
	v_pk_mul_f32 v[242:243], v[56:57], v[206:207] op_sel_hi:[1,0]
	v_pk_mul_f32 v[244:245], v[58:59], v[206:207] op_sel_hi:[1,0]
	s_mov_b32 s98, 0x5808
	s_mov_b32 s99, 0
	v_cvt_pk_bf16_f32 v242, v242, v243
	v_cvt_pk_bf16_f32 v243, v244, v245
	v_lshl_add_u64 v[150:151], v[246:247], 0, s[98:99]
	global_store_dwordx2 v[150:151], v[242:243], off
	s_or_b64 exec, exec, s[6:7]
	v_pk_mul_f32 v[60:61], v[60:61], v[206:207] op_sel_hi:[1,0]
	v_pk_mul_f32 v[62:63], v[62:63], v[206:207] op_sel_hi:[1,0]
	v_pk_mul_f32 v[56:57], v[56:57], v[208:209] op_sel_hi:[1,0]
	v_pk_mul_f32 v[58:59], v[58:59], v[208:209] op_sel_hi:[1,0]
	v_pk_fma_f32 v[146:147], v[200:201], v[60:61], v[238:239]
	v_pk_fma_f32 v[148:149], v[202:203], v[62:63], v[240:241]
	v_fmac_f32_dpp v146, v60, v196 row_shr:1 row_mask:0xf bank_mask:0xf bound_ctrl:1
	v_fmac_f32_dpp v147, v61, v197 row_shr:1 row_mask:0xf bank_mask:0xf bound_ctrl:1
	v_fmac_f32_dpp v148, v62, v198 row_shr:1 row_mask:0xf bank_mask:0xf bound_ctrl:1
	v_fmac_f32_dpp v149, v63, v199 row_shr:1 row_mask:0xf bank_mask:0xf bound_ctrl:1
	v_fmac_f32_dpp v146, v60, v192 row_shr:2 row_mask:0xf bank_mask:0xf bound_ctrl:1
	v_fmac_f32_dpp v147, v61, v193 row_shr:2 row_mask:0xf bank_mask:0xf bound_ctrl:1
	v_fmac_f32_dpp v148, v62, v194 row_shr:2 row_mask:0xf bank_mask:0xf bound_ctrl:1
	v_fmac_f32_dpp v149, v63, v195 row_shr:2 row_mask:0xf bank_mask:0xf bound_ctrl:1
	v_exp_f32_e32 v242, v146
	v_exp_f32_e32 v243, v147
	v_exp_f32_e32 v244, v148
	v_exp_f32_e32 v245, v149
	v_pk_mul_f32 v[146:147], v[146:147], v[56:57]
	v_pk_mul_f32 v[148:149], v[148:149], v[58:59]
	v_pk_add_f32 v[242:243], v[242:243], 1.0 op_sel_hi:[1,0]
	v_pk_add_f32 v[244:245], v[244:245], 1.0 op_sel_hi:[1,0]
	v_rcp_f32_e32 v242, v242
	v_rcp_f32_e32 v243, v243
	v_rcp_f32_e32 v244, v244
	v_rcp_f32_e32 v245, v245
	v_cvt_pk_bf16_f32 v56, v60, v61
	v_cvt_pk_bf16_f32 v57, v62, v63
	v_pk_mul_f32 v[146:147], v[146:147], v[242:243]
	v_pk_mul_f32 v[148:149], v[148:149], v[244:245]
	s_mov_b32 s98, 0x2c08
	s_mov_b32 s99, 0
	s_and_saveexec_b64 s[6:7], s[40:41]
	v_lshl_add_u64 v[150:151], v[246:247], 0, s[98:99]
	global_store_dwordx2 v[150:151], v[56:57], off
	s_or_b64 exec, exec, s[6:7]
	v_cvt_pk_bf16_f32 v126, v146, v147
	v_cvt_pk_bf16_f32 v127, v148, v149
	s_mov_b32 s5, 0x0
	s_and_saveexec_b64 s[6:7], s[38:39]
	buffer_store_dwordx4 v[124:127], v185, s[52:55], s5 offen sc1
	s_or_b64 exec, exec, s[6:7]
	v_pk_mul_f32 v[52:53], v[52:53], v[210:211] op_sel_hi:[1,0]
	v_pk_mul_f32 v[54:55], v[54:55], v[210:211] op_sel_hi:[1,0]
	v_pk_mul_f32 v[48:49], v[48:49], v[212:213] op_sel_hi:[1,0]
	v_pk_mul_f32 v[50:51], v[50:51], v[212:213] op_sel_hi:[1,0]
	v_pk_fma_f32 v[146:147], v[200:201], v[52:53], v[238:239]
	v_pk_fma_f32 v[148:149], v[202:203], v[54:55], v[240:241]
	v_fmac_f32_dpp v146, v52, v196 row_shr:1 row_mask:0xf bank_mask:0xf bound_ctrl:1
	v_fmac_f32_dpp v147, v53, v197 row_shr:1 row_mask:0xf bank_mask:0xf bound_ctrl:1
	v_fmac_f32_dpp v148, v54, v198 row_shr:1 row_mask:0xf bank_mask:0xf bound_ctrl:1
	v_fmac_f32_dpp v149, v55, v199 row_shr:1 row_mask:0xf bank_mask:0xf bound_ctrl:1
	v_fmac_f32_dpp v146, v60, v196 row_shl:15 row_mask:0xf bank_mask:0xf
	v_fmac_f32_dpp v147, v61, v197 row_shl:15 row_mask:0xf bank_mask:0xf
	v_fmac_f32_dpp v148, v62, v198 row_shl:15 row_mask:0xf bank_mask:0xf
	v_fmac_f32_dpp v149, v63, v199 row_shl:15 row_mask:0xf bank_mask:0xf
	v_fmac_f32_dpp v146, v52, v192 row_shr:2 row_mask:0xf bank_mask:0xf bound_ctrl:1
	v_fmac_f32_dpp v147, v53, v193 row_shr:2 row_mask:0xf bank_mask:0xf bound_ctrl:1
	v_fmac_f32_dpp v148, v54, v194 row_shr:2 row_mask:0xf bank_mask:0xf bound_ctrl:1
	v_fmac_f32_dpp v149, v55, v195 row_shr:2 row_mask:0xf bank_mask:0xf bound_ctrl:1
	v_fmac_f32_dpp v146, v60, v192 row_shl:14 row_mask:0xf bank_mask:0xf
	v_fmac_f32_dpp v147, v61, v193 row_shl:14 row_mask:0xf bank_mask:0xf
	v_fmac_f32_dpp v148, v62, v194 row_shl:14 row_mask:0xf bank_mask:0xf
	v_fmac_f32_dpp v149, v63, v195 row_shl:14 row_mask:0xf bank_mask:0xf
	v_exp_f32_e32 v242, v146
	v_exp_f32_e32 v243, v147
	v_exp_f32_e32 v244, v148
	v_exp_f32_e32 v245, v149
	v_pk_mul_f32 v[146:147], v[146:147], v[48:49]
	v_pk_mul_f32 v[148:149], v[148:149], v[50:51]
	v_pk_add_f32 v[242:243], v[242:243], 1.0 op_sel_hi:[1,0]
	v_pk_add_f32 v[244:245], v[244:245], 1.0 op_sel_hi:[1,0]
	v_rcp_f32_e32 v242, v242
	v_rcp_f32_e32 v243, v243
	v_rcp_f32_e32 v244, v244
	v_rcp_f32_e32 v245, v245
	s_nop 0
	v_pk_mul_f32 v[146:147], v[146:147], v[242:243]
	v_pk_mul_f32 v[148:149], v[148:149], v[244:245]
	v_cvt_pk_bf16_f32 v118, v146, v147
	v_cvt_pk_bf16_f32 v119, v148, v149
	s_mov_b32 s5, 0x16000
	buffer_store_dwordx4 v[116:119], v185, s[52:55], s5 offen sc1
	v_pk_mul_f32 v[44:45], v[44:45], v[214:215] op_sel_hi:[1,0]
	v_pk_mul_f32 v[46:47], v[46:47], v[214:215] op_sel_hi:[1,0]
	v_pk_mul_f32 v[40:41], v[40:41], v[216:217] op_sel_hi:[1,0]
	v_pk_mul_f32 v[42:43], v[42:43], v[216:217] op_sel_hi:[1,0]
	v_pk_fma_f32 v[146:147], v[200:201], v[44:45], v[238:239]
	v_pk_fma_f32 v[148:149], v[202:203], v[46:47], v[240:241]
	v_fmac_f32_dpp v146, v44, v196 row_shr:1 row_mask:0xf bank_mask:0xf bound_ctrl:1
	v_fmac_f32_dpp v147, v45, v197 row_shr:1 row_mask:0xf bank_mask:0xf bound_ctrl:1
	v_fmac_f32_dpp v148, v46, v198 row_shr:1 row_mask:0xf bank_mask:0xf bound_ctrl:1
	v_fmac_f32_dpp v149, v47, v199 row_shr:1 row_mask:0xf bank_mask:0xf bound_ctrl:1
	v_fmac_f32_dpp v146, v52, v196 row_shl:15 row_mask:0xf bank_mask:0xf
	v_fmac_f32_dpp v147, v53, v197 row_shl:15 row_mask:0xf bank_mask:0xf
	v_fmac_f32_dpp v148, v54, v198 row_shl:15 row_mask:0xf bank_mask:0xf
	v_fmac_f32_dpp v149, v55, v199 row_shl:15 row_mask:0xf bank_mask:0xf
	v_fmac_f32_dpp v146, v44, v192 row_shr:2 row_mask:0xf bank_mask:0xf bound_ctrl:1
	v_fmac_f32_dpp v147, v45, v193 row_shr:2 row_mask:0xf bank_mask:0xf bound_ctrl:1
	v_fmac_f32_dpp v148, v46, v194 row_shr:2 row_mask:0xf bank_mask:0xf bound_ctrl:1
	v_fmac_f32_dpp v149, v47, v195 row_shr:2 row_mask:0xf bank_mask:0xf bound_ctrl:1
	v_fmac_f32_dpp v146, v52, v192 row_shl:14 row_mask:0xf bank_mask:0xf
	v_fmac_f32_dpp v147, v53, v193 row_shl:14 row_mask:0xf bank_mask:0xf
	v_fmac_f32_dpp v148, v54, v194 row_shl:14 row_mask:0xf bank_mask:0xf
	v_fmac_f32_dpp v149, v55, v195 row_shl:14 row_mask:0xf bank_mask:0xf
	v_exp_f32_e32 v242, v146
	v_exp_f32_e32 v243, v147
	v_exp_f32_e32 v244, v148
	v_exp_f32_e32 v245, v149
	v_pk_mul_f32 v[146:147], v[146:147], v[40:41]
	v_pk_mul_f32 v[148:149], v[148:149], v[42:43]
	v_pk_add_f32 v[242:243], v[242:243], 1.0 op_sel_hi:[1,0]
	v_pk_add_f32 v[244:245], v[244:245], 1.0 op_sel_hi:[1,0]
	v_rcp_f32_e32 v242, v242
	v_rcp_f32_e32 v243, v243
	v_rcp_f32_e32 v244, v244
	v_rcp_f32_e32 v245, v245
	s_nop 0
	v_pk_mul_f32 v[146:147], v[146:147], v[242:243]
	v_pk_mul_f32 v[148:149], v[148:149], v[244:245]
	v_cvt_pk_bf16_f32 v100, v146, v147
	v_cvt_pk_bf16_f32 v101, v148, v149
	s_mov_b32 s5, 0x2c000
	buffer_store_dwordx4 v[98:101], v185, s[52:55], s5 offen sc1
	v_pk_mul_f32 v[36:37], v[36:37], v[218:219] op_sel_hi:[1,0]
	v_pk_mul_f32 v[38:39], v[38:39], v[218:219] op_sel_hi:[1,0]
	v_pk_mul_f32 v[32:33], v[32:33], v[220:221] op_sel_hi:[1,0]
	v_pk_mul_f32 v[34:35], v[34:35], v[220:221] op_sel_hi:[1,0]
	v_pk_fma_f32 v[146:147], v[200:201], v[36:37], v[238:239]
	v_pk_fma_f32 v[148:149], v[202:203], v[38:39], v[240:241]
	v_fmac_f32_dpp v146, v36, v196 row_shr:1 row_mask:0xf bank_mask:0xf bound_ctrl:1
	v_fmac_f32_dpp v147, v37, v197 row_shr:1 row_mask:0xf bank_mask:0xf bound_ctrl:1
	v_fmac_f32_dpp v148, v38, v198 row_shr:1 row_mask:0xf bank_mask:0xf bound_ctrl:1
	v_fmac_f32_dpp v149, v39, v199 row_shr:1 row_mask:0xf bank_mask:0xf bound_ctrl:1
	v_fmac_f32_dpp v146, v44, v196 row_shl:15 row_mask:0xf bank_mask:0xf
	v_fmac_f32_dpp v147, v45, v197 row_shl:15 row_mask:0xf bank_mask:0xf
	v_fmac_f32_dpp v148, v46, v198 row_shl:15 row_mask:0xf bank_mask:0xf
	v_fmac_f32_dpp v149, v47, v199 row_shl:15 row_mask:0xf bank_mask:0xf
	v_fmac_f32_dpp v146, v36, v192 row_shr:2 row_mask:0xf bank_mask:0xf bound_ctrl:1
	v_fmac_f32_dpp v147, v37, v193 row_shr:2 row_mask:0xf bank_mask:0xf bound_ctrl:1
	v_fmac_f32_dpp v148, v38, v194 row_shr:2 row_mask:0xf bank_mask:0xf bound_ctrl:1
	v_fmac_f32_dpp v149, v39, v195 row_shr:2 row_mask:0xf bank_mask:0xf bound_ctrl:1
	v_fmac_f32_dpp v146, v44, v192 row_shl:14 row_mask:0xf bank_mask:0xf
	v_fmac_f32_dpp v147, v45, v193 row_shl:14 row_mask:0xf bank_mask:0xf
	v_fmac_f32_dpp v148, v46, v194 row_shl:14 row_mask:0xf bank_mask:0xf
	v_fmac_f32_dpp v149, v47, v195 row_shl:14 row_mask:0xf bank_mask:0xf
	v_exp_f32_e32 v242, v146
	v_exp_f32_e32 v243, v147
	v_exp_f32_e32 v244, v148
	v_exp_f32_e32 v245, v149
	v_pk_mul_f32 v[146:147], v[146:147], v[32:33]
	v_pk_mul_f32 v[148:149], v[148:149], v[34:35]
	v_pk_add_f32 v[242:243], v[242:243], 1.0 op_sel_hi:[1,0]
	v_pk_add_f32 v[244:245], v[244:245], 1.0 op_sel_hi:[1,0]
	v_rcp_f32_e32 v242, v242
	v_rcp_f32_e32 v243, v243
	v_rcp_f32_e32 v244, v244
	v_rcp_f32_e32 v245, v245
	v_cvt_pk_bf16_f32 v32, v36, v37
	v_cvt_pk_bf16_f32 v33, v38, v39
	v_pk_mul_f32 v[146:147], v[146:147], v[242:243]
	v_pk_mul_f32 v[148:149], v[148:149], v[244:245]
	s_mov_b32 s98, 0xfffecc08
	s_mov_b32 s99, -1
	s_and_saveexec_b64 s[6:7], s[42:43]
	v_lshl_add_u64 v[150:151], v[246:247], 0, s[98:99]
	global_store_dwordx2 v[150:151], v[32:33], off
	s_or_b64 exec, exec, s[6:7]
	v_cvt_pk_bf16_f32 v106, v146, v147
	v_cvt_pk_bf16_f32 v107, v148, v149
	s_mov_b32 s5, 0x42000
	buffer_store_dwordx4 v[104:107], v185, s[52:55], s5 offen sc1
	s_and_saveexec_b64 s[6:7], s[40:41]
	v_pk_mul_f32 v[242:243], v[24:25], v[222:223] op_sel_hi:[1,0]
	v_pk_mul_f32 v[244:245], v[26:27], v[222:223] op_sel_hi:[1,0]
	s_mov_b32 s98, 0x16008
	s_mov_b32 s99, 0
	v_cvt_pk_bf16_f32 v242, v242, v243
	v_cvt_pk_bf16_f32 v243, v244, v245
	v_lshl_add_u64 v[150:151], v[246:247], 0, s[98:99]
	global_store_dwordx2 v[150:151], v[242:243], off
	s_or_b64 exec, exec, s[6:7]
	v_pk_mul_f32 v[28:29], v[28:29], v[222:223] op_sel_hi:[1,0]
	v_pk_mul_f32 v[30:31], v[30:31], v[222:223] op_sel_hi:[1,0]
	v_pk_mul_f32 v[24:25], v[24:25], v[224:225] op_sel_hi:[1,0]
	v_pk_mul_f32 v[26:27], v[26:27], v[224:225] op_sel_hi:[1,0]
	v_pk_fma_f32 v[146:147], v[200:201], v[28:29], v[238:239]
	v_pk_fma_f32 v[148:149], v[202:203], v[30:31], v[240:241]
	v_fmac_f32_dpp v146, v28, v196 row_shr:1 row_mask:0xf bank_mask:0xf bound_ctrl:1
	v_fmac_f32_dpp v147, v29, v197 row_shr:1 row_mask:0xf bank_mask:0xf bound_ctrl:1
	v_fmac_f32_dpp v148, v30, v198 row_shr:1 row_mask:0xf bank_mask:0xf bound_ctrl:1
	v_fmac_f32_dpp v149, v31, v199 row_shr:1 row_mask:0xf bank_mask:0xf bound_ctrl:1
	v_fmac_f32_dpp v146, v28, v192 row_shr:2 row_mask:0xf bank_mask:0xf bound_ctrl:1
	v_fmac_f32_dpp v147, v29, v193 row_shr:2 row_mask:0xf bank_mask:0xf bound_ctrl:1
	v_fmac_f32_dpp v148, v30, v194 row_shr:2 row_mask:0xf bank_mask:0xf bound_ctrl:1
	v_fmac_f32_dpp v149, v31, v195 row_shr:2 row_mask:0xf bank_mask:0xf bound_ctrl:1
	v_exp_f32_e32 v242, v146
	v_exp_f32_e32 v243, v147
	v_exp_f32_e32 v244, v148
	v_exp_f32_e32 v245, v149
	v_pk_mul_f32 v[146:147], v[146:147], v[24:25]
	v_pk_mul_f32 v[148:149], v[148:149], v[26:27]
	v_pk_add_f32 v[242:243], v[242:243], 1.0 op_sel_hi:[1,0]
	v_pk_add_f32 v[244:245], v[244:245], 1.0 op_sel_hi:[1,0]
	v_rcp_f32_e32 v242, v242
	v_rcp_f32_e32 v243, v243
	v_rcp_f32_e32 v244, v244
	v_rcp_f32_e32 v245, v245
	v_cvt_pk_bf16_f32 v24, v28, v29
	v_cvt_pk_bf16_f32 v25, v30, v31
	v_pk_mul_f32 v[146:147], v[146:147], v[242:243]
	v_pk_mul_f32 v[148:149], v[148:149], v[244:245]
	s_mov_b32 s98, 0x13408
	s_mov_b32 s99, 0
	s_and_saveexec_b64 s[6:7], s[40:41]
	v_lshl_add_u64 v[150:151], v[246:247], 0, s[98:99]
	global_store_dwordx2 v[150:151], v[24:25], off
	s_or_b64 exec, exec, s[6:7]
	v_cvt_pk_bf16_f32 v90, v146, v147
	v_cvt_pk_bf16_f32 v91, v148, v149
	s_mov_b32 s5, 0xb0000
	s_and_saveexec_b64 s[6:7], s[38:39]
	buffer_store_dwordx4 v[88:91], v185, s[52:55], s5 offen sc1
	s_or_b64 exec, exec, s[6:7]
	v_pk_mul_f32 v[20:21], v[20:21], v[226:227] op_sel_hi:[1,0]
	v_pk_mul_f32 v[22:23], v[22:23], v[226:227] op_sel_hi:[1,0]
	v_pk_mul_f32 v[16:17], v[16:17], v[228:229] op_sel_hi:[1,0]
	v_pk_mul_f32 v[18:19], v[18:19], v[228:229] op_sel_hi:[1,0]
	v_pk_fma_f32 v[146:147], v[200:201], v[20:21], v[238:239]
	v_pk_fma_f32 v[148:149], v[202:203], v[22:23], v[240:241]
	v_fmac_f32_dpp v146, v20, v196 row_shr:1 row_mask:0xf bank_mask:0xf bound_ctrl:1
	v_fmac_f32_dpp v147, v21, v197 row_shr:1 row_mask:0xf bank_mask:0xf bound_ctrl:1
	v_fmac_f32_dpp v148, v22, v198 row_shr:1 row_mask:0xf bank_mask:0xf bound_ctrl:1
	v_fmac_f32_dpp v149, v23, v199 row_shr:1 row_mask:0xf bank_mask:0xf bound_ctrl:1
	v_fmac_f32_dpp v146, v28, v196 row_shl:15 row_mask:0xf bank_mask:0xf
	v_fmac_f32_dpp v147, v29, v197 row_shl:15 row_mask:0xf bank_mask:0xf
	v_fmac_f32_dpp v148, v30, v198 row_shl:15 row_mask:0xf bank_mask:0xf
	v_fmac_f32_dpp v149, v31, v199 row_shl:15 row_mask:0xf bank_mask:0xf
	v_fmac_f32_dpp v146, v20, v192 row_shr:2 row_mask:0xf bank_mask:0xf bound_ctrl:1
	v_fmac_f32_dpp v147, v21, v193 row_shr:2 row_mask:0xf bank_mask:0xf bound_ctrl:1
	v_fmac_f32_dpp v148, v22, v194 row_shr:2 row_mask:0xf bank_mask:0xf bound_ctrl:1
	v_fmac_f32_dpp v149, v23, v195 row_shr:2 row_mask:0xf bank_mask:0xf bound_ctrl:1
	v_fmac_f32_dpp v146, v28, v192 row_shl:14 row_mask:0xf bank_mask:0xf
	v_fmac_f32_dpp v147, v29, v193 row_shl:14 row_mask:0xf bank_mask:0xf
	v_fmac_f32_dpp v148, v30, v194 row_shl:14 row_mask:0xf bank_mask:0xf
	v_fmac_f32_dpp v149, v31, v195 row_shl:14 row_mask:0xf bank_mask:0xf
	v_exp_f32_e32 v242, v146
	v_exp_f32_e32 v243, v147
	v_exp_f32_e32 v244, v148
	v_exp_f32_e32 v245, v149
	v_pk_mul_f32 v[146:147], v[146:147], v[16:17]
	v_pk_mul_f32 v[148:149], v[148:149], v[18:19]
	v_pk_add_f32 v[242:243], v[242:243], 1.0 op_sel_hi:[1,0]
	v_pk_add_f32 v[244:245], v[244:245], 1.0 op_sel_hi:[1,0]
	v_rcp_f32_e32 v242, v242
	v_rcp_f32_e32 v243, v243
	v_rcp_f32_e32 v244, v244
	v_rcp_f32_e32 v245, v245
	s_nop 0
	v_pk_mul_f32 v[146:147], v[146:147], v[242:243]
	v_pk_mul_f32 v[148:149], v[148:149], v[244:245]
	v_cvt_pk_bf16_f32 v82, v146, v147
	v_cvt_pk_bf16_f32 v83, v148, v149
	s_mov_b32 s5, 0xc6000
	buffer_store_dwordx4 v[80:83], v185, s[52:55], s5 offen sc1
	v_pk_mul_f32 v[12:13], v[12:13], v[230:231] op_sel_hi:[1,0]
	v_pk_mul_f32 v[14:15], v[14:15], v[230:231] op_sel_hi:[1,0]
	v_pk_mul_f32 v[8:9], v[8:9], v[232:233] op_sel_hi:[1,0]
	v_pk_mul_f32 v[10:11], v[10:11], v[232:233] op_sel_hi:[1,0]
	v_pk_fma_f32 v[146:147], v[200:201], v[12:13], v[238:239]
	v_pk_fma_f32 v[148:149], v[202:203], v[14:15], v[240:241]
	v_fmac_f32_dpp v146, v12, v196 row_shr:1 row_mask:0xf bank_mask:0xf bound_ctrl:1
	v_fmac_f32_dpp v147, v13, v197 row_shr:1 row_mask:0xf bank_mask:0xf bound_ctrl:1
	v_fmac_f32_dpp v148, v14, v198 row_shr:1 row_mask:0xf bank_mask:0xf bound_ctrl:1
	v_fmac_f32_dpp v149, v15, v199 row_shr:1 row_mask:0xf bank_mask:0xf bound_ctrl:1
	v_fmac_f32_dpp v146, v20, v196 row_shl:15 row_mask:0xf bank_mask:0xf
	v_fmac_f32_dpp v147, v21, v197 row_shl:15 row_mask:0xf bank_mask:0xf
	v_fmac_f32_dpp v148, v22, v198 row_shl:15 row_mask:0xf bank_mask:0xf
	v_fmac_f32_dpp v149, v23, v199 row_shl:15 row_mask:0xf bank_mask:0xf
	v_fmac_f32_dpp v146, v12, v192 row_shr:2 row_mask:0xf bank_mask:0xf bound_ctrl:1
	v_fmac_f32_dpp v147, v13, v193 row_shr:2 row_mask:0xf bank_mask:0xf bound_ctrl:1
	v_fmac_f32_dpp v148, v14, v194 row_shr:2 row_mask:0xf bank_mask:0xf bound_ctrl:1
	v_fmac_f32_dpp v149, v15, v195 row_shr:2 row_mask:0xf bank_mask:0xf bound_ctrl:1
	v_fmac_f32_dpp v146, v20, v192 row_shl:14 row_mask:0xf bank_mask:0xf
	v_fmac_f32_dpp v147, v21, v193 row_shl:14 row_mask:0xf bank_mask:0xf
	v_fmac_f32_dpp v148, v22, v194 row_shl:14 row_mask:0xf bank_mask:0xf
	v_fmac_f32_dpp v149, v23, v195 row_shl:14 row_mask:0xf bank_mask:0xf
	v_exp_f32_e32 v242, v146
	v_exp_f32_e32 v243, v147
	v_exp_f32_e32 v244, v148
	v_exp_f32_e32 v245, v149
	v_pk_mul_f32 v[146:147], v[146:147], v[8:9]
	v_pk_mul_f32 v[148:149], v[148:149], v[10:11]
	v_pk_add_f32 v[242:243], v[242:243], 1.0 op_sel_hi:[1,0]
	v_pk_add_f32 v[244:245], v[244:245], 1.0 op_sel_hi:[1,0]
	v_rcp_f32_e32 v242, v242
	v_rcp_f32_e32 v243, v243
	v_rcp_f32_e32 v244, v244
	v_rcp_f32_e32 v245, v245
	s_nop 0
	v_pk_mul_f32 v[146:147], v[146:147], v[242:243]
	v_pk_mul_f32 v[148:149], v[148:149], v[244:245]
	v_cvt_pk_bf16_f32 v74, v146, v147
	v_cvt_pk_bf16_f32 v75, v148, v149
	s_mov_b32 s5, 0xdc000
	buffer_store_dwordx4 v[72:75], v185, s[52:55], s5 offen sc1
	v_pk_mul_f32 v[4:5], v[4:5], v[234:235] op_sel_hi:[1,0]
	v_pk_mul_f32 v[6:7], v[6:7], v[234:235] op_sel_hi:[1,0]
	v_pk_mul_f32 v[0:1], v[0:1], v[236:237] op_sel_hi:[1,0]
	v_pk_mul_f32 v[2:3], v[2:3], v[236:237] op_sel_hi:[1,0]
	v_pk_fma_f32 v[146:147], v[200:201], v[4:5], v[238:239]
	v_pk_fma_f32 v[148:149], v[202:203], v[6:7], v[240:241]
	v_fmac_f32_dpp v146, v4, v196 row_shr:1 row_mask:0xf bank_mask:0xf bound_ctrl:1
	v_fmac_f32_dpp v147, v5, v197 row_shr:1 row_mask:0xf bank_mask:0xf bound_ctrl:1
	v_fmac_f32_dpp v148, v6, v198 row_shr:1 row_mask:0xf bank_mask:0xf bound_ctrl:1
	v_fmac_f32_dpp v149, v7, v199 row_shr:1 row_mask:0xf bank_mask:0xf bound_ctrl:1
	v_fmac_f32_dpp v146, v12, v196 row_shl:15 row_mask:0xf bank_mask:0xf
	v_fmac_f32_dpp v147, v13, v197 row_shl:15 row_mask:0xf bank_mask:0xf
	v_fmac_f32_dpp v148, v14, v198 row_shl:15 row_mask:0xf bank_mask:0xf
	v_fmac_f32_dpp v149, v15, v199 row_shl:15 row_mask:0xf bank_mask:0xf
	v_fmac_f32_dpp v146, v4, v192 row_shr:2 row_mask:0xf bank_mask:0xf bound_ctrl:1
	v_fmac_f32_dpp v147, v5, v193 row_shr:2 row_mask:0xf bank_mask:0xf bound_ctrl:1
	v_fmac_f32_dpp v148, v6, v194 row_shr:2 row_mask:0xf bank_mask:0xf bound_ctrl:1
	v_fmac_f32_dpp v149, v7, v195 row_shr:2 row_mask:0xf bank_mask:0xf bound_ctrl:1
	v_fmac_f32_dpp v146, v12, v192 row_shl:14 row_mask:0xf bank_mask:0xf
	v_fmac_f32_dpp v147, v13, v193 row_shl:14 row_mask:0xf bank_mask:0xf
	v_fmac_f32_dpp v148, v14, v194 row_shl:14 row_mask:0xf bank_mask:0xf
	v_fmac_f32_dpp v149, v15, v195 row_shl:14 row_mask:0xf bank_mask:0xf
	v_exp_f32_e32 v242, v146
	v_exp_f32_e32 v243, v147
	v_exp_f32_e32 v244, v148
	v_exp_f32_e32 v245, v149
	v_pk_mul_f32 v[146:147], v[146:147], v[0:1]
	v_pk_mul_f32 v[148:149], v[148:149], v[2:3]
	v_pk_add_f32 v[242:243], v[242:243], 1.0 op_sel_hi:[1,0]
	v_pk_add_f32 v[244:245], v[244:245], 1.0 op_sel_hi:[1,0]
	v_rcp_f32_e32 v242, v242
	v_rcp_f32_e32 v243, v243
	v_rcp_f32_e32 v244, v244
	v_rcp_f32_e32 v245, v245
	v_cvt_pk_bf16_f32 v0, v4, v5
	v_cvt_pk_bf16_f32 v1, v6, v7
	v_pk_mul_f32 v[146:147], v[146:147], v[242:243]
	v_pk_mul_f32 v[148:149], v[148:149], v[244:245]
	s_mov_b32 s98, 0xffffd408
	s_mov_b32 s99, -1
	s_and_saveexec_b64 s[6:7], s[42:43]
	v_lshl_add_u64 v[150:151], v[246:247], 0, s[98:99]
	global_store_dwordx2 v[150:151], v[0:1], off
	s_or_b64 exec, exec, s[6:7]
	v_cvt_pk_bf16_f32 v66, v146, v147
	v_cvt_pk_bf16_f32 v67, v148, v149
	s_mov_b32 s5, 0xf2000
	buffer_store_dwordx4 v[64:67], v185, s[52:55], s5 offen sc1
	s_andn2_b64 vcc, exec, s[44:45]
	s_mov_b64 s[6:7], -1
	s_cbranch_vccnz .LBB0_716
	s_andn2_b64 vcc, exec, s[28:29]
	s_cbranch_vccnz .LBB0_715
	s_barrier
	s_branch .LBB0_715

	.amdhsa_kernel _Z6mk_fwd4Args
		.amdhsa_group_segment_fixed_size 0
		.amdhsa_private_segment_fixed_size 0
		.amdhsa_kernarg_size 456
		.amdhsa_user_sgpr_count 2
		.amdhsa_user_sgpr_dispatch_ptr 0
		.amdhsa_user_sgpr_queue_ptr 0
		.amdhsa_user_sgpr_kernarg_segment_ptr 1
		.amdhsa_user_sgpr_dispatch_id 0
		.amdhsa_user_sgpr_kernarg_preload_length 0
		.amdhsa_user_sgpr_kernarg_preload_offset 0
		.amdhsa_user_sgpr_private_segment_size 0
		.amdhsa_uses_dynamic_stack 0
		.amdhsa_enable_private_segment 0
		.amdhsa_system_sgpr_workgroup_id_x 1
		.amdhsa_system_sgpr_workgroup_id_y 0
		.amdhsa_system_sgpr_workgroup_id_z 0
		.amdhsa_system_sgpr_workgroup_info 0
		.amdhsa_system_vgpr_workitem_id 2
		.amdhsa_next_free_vgpr 251
		.amdhsa_next_free_sgpr 102
		.amdhsa_accum_offset 252
		.amdhsa_reserve_vcc 1
		.amdhsa_float_round_mode_32 0
		.amdhsa_float_round_mode_16_64 0
		.amdhsa_float_denorm_mode_32 3
		.amdhsa_float_denorm_mode_16_64 3
		.amdhsa_dx10_clamp 1
		.amdhsa_ieee_mode 1
		.amdhsa_fp16_overflow 0
		.amdhsa_tg_split 0
		.amdhsa_exception_fp_ieee_invalid_op 0
		.amdhsa_exception_fp_denorm_src 0
		.amdhsa_exception_fp_ieee_div_zero 0
		.amdhsa_exception_fp_ieee_overflow 0
		.amdhsa_exception_fp_ieee_underflow 0
		.amdhsa_exception_fp_ieee_inexact 0
		.amdhsa_exception_int_div_zero 0
	.end_amdhsa_kernel

amdhsa.kernels:
  - .agpr_count:     0
    .args:
      - .offset:         0
        .size:           200
        .value_kind:     by_value
      - .offset:         200
        .size:           4
        .value_kind:     hidden_block_count_x
      - .offset:         204
        .size:           4
        .value_kind:     hidden_block_count_y
      - .offset:         208
        .size:           4
        .value_kind:     hidden_block_count_z
      - .offset:         212
        .size:           2
        .value_kind:     hidden_group_size_x
      - .offset:         214
        .size:           2
        .value_kind:     hidden_group_size_y
      - .offset:         216
        .size:           2
        .value_kind:     hidden_group_size_z
      - .offset:         218
        .size:           2
        .value_kind:     hidden_remainder_x
      - .offset:         220
        .size:           2
        .value_kind:     hidden_remainder_y
      - .offset:         222
        .size:           2
        .value_kind:     hidden_remainder_z
      - .offset:         240
        .size:           8
        .value_kind:     hidden_global_offset_x
      - .offset:         248
        .size:           8
        .value_kind:     hidden_global_offset_y
      - .offset:         256
        .size:           8
        .value_kind:     hidden_global_offset_z
      - .offset:         264
        .size:           2
        .value_kind:     hidden_grid_dims
      - .offset:         288
        .size:           8
        .value_kind:     hidden_multigrid_sync_arg
      - .offset:         320
        .size:           4
        .value_kind:     hidden_dynamic_lds_size
    .group_segment_fixed_size: 0
    .kernarg_segment_align: 8
    .kernarg_segment_size: 456
    .language:       OpenCL C
    .language_version:
      - 2
      - 0
    .max_flat_workgroup_size: 512
    .name:           _Z6mk_fwd4Args
    .private_segment_fixed_size: 0
    .sgpr_count:     108
    .sgpr_spill_count: 149
    .symbol:         _Z6mk_fwd4Args.kd
    .uniform_work_group_size: 1
    .uses_dynamic_stack: false
    .vgpr_count:     251
    .vgpr_spill_count: 0
    .wavefront_size: 64
